# LN1 gamma/beta loads hoisted out of the row loop as well (on top of v20)
# baseline (speedup 1.0000x reference)
; __device__ __forceinline__ void ln_phase(const Params& P, const float* g, const float* b, bf16_t* xb) {
;     const int lane = threadIdx.x & 63;
;     const int gw = blockIdx.x * 8 + (threadIdx.x >> 6), nw = gridDim.x * 8;
;     for (int row = gw; row < NTOK; row += nw) {
;         float* y = P.out + O_Y + (size_t)row * 2048;
;         float4 v[8]; float s = 0.f;
; #pragma unroll
;         for (int i = 0; i < 8; ++i) { v[i] = *(const float4*)(y + (i * 64 + lane) * 4); s += (v[i].x + v[i].y) + (v[i].z + v[i].w); }
;         s = halfsum32(s); s += __shfl_xor(s, 32);
;         const float mu = s * (1.0f / 2048.0f); float q = 0.f;
; #pragma unroll
;         for (int i = 0; i < 8; ++i) { v[i].x -= mu; v[i].y -= mu; v[i].z -= mu; v[i].w -= mu; q += (v[i].x * v[i].x + v[i].y * v[i].y) + (v[i].z * v[i].z + v[i].w * v[i].w); }
;         q = halfsum32(q); q += __shfl_xor(q, 32);
;         const float rstd = rsqrtf(q * (1.0f / 2048.0f) + 1e-5f);
; #pragma unroll
;         for (int i = 0; i < 8; ++i) { const int c = (i * 64 + lane) * 4; const float4 gg = *(const float4*)(g + c), bb = *(const float4*)(b + c);
.LBB0_2648:
	s_or_b64 exec, exec, s[0:1]
	v_readlane_b32 s0, v252, 8
	v_lshrrev_b32_e32 v0, 6, v200
	v_readlane_b32 s1, v252, 9
	v_add_u32_e32 v124, s3, v0
	s_movk_i32 s1, 0x4200
	s_lshl_b32 s0, s0, 3
	v_cmp_gt_i32_e64 s[4:5], s1, v124
	v_ashrrev_i32_e32 v125, 31, v124
	v_lshlrev_b32_e32 v144, 4, v200
	s_waitcnt lgkmcnt(0)
	s_barrier
	s_and_saveexec_b64 s[8:9], s[4:5]
	s_cbranch_execz .LBB0_2667
	v_and_b32_e32 v1, 64, v210
	v_xor_b32_e32 v0, 1, v210
	v_add_u32_e32 v1, 64, v1
	v_cmp_lt_i32_e32 vcc, v0, v1
	v_readlane_b32 s12, v252, 16
	v_readlane_b32 s13, v252, 17
	v_cndmask_b32_e32 v0, v210, v0, vcc
	v_lshlrev_b32_e32 v58, 2, v0
	v_xor_b32_e32 v0, 2, v210
	v_cmp_lt_i32_e32 vcc, v0, v1
	v_readlane_b32 s22, v252, 26
	v_readlane_b32 s23, v252, 27
	v_cndmask_b32_e32 v0, v210, v0, vcc
	v_lshlrev_b32_e32 v59, 2, v0
	v_xor_b32_e32 v0, 4, v210
	v_cmp_lt_i32_e32 vcc, v0, v1
	v_readlane_b32 s24, v252, 28
	v_readlane_b32 s25, v252, 29
	v_cndmask_b32_e32 v0, v210, v0, vcc
	v_lshlrev_b32_e32 v60, 2, v0
	v_xor_b32_e32 v0, 8, v210
	v_cmp_lt_i32_e32 vcc, v0, v1
	s_mov_b64 s[10:11], s[22:23]
	s_mov_b64 s[12:13], s[24:25]
	v_cndmask_b32_e32 v0, v210, v0, vcc
	v_lshlrev_b32_e32 v61, 2, v0
	v_xor_b32_e32 v0, 16, v210
	v_cmp_lt_i32_e32 vcc, v0, v1
	s_mov_b64 s[6:7], 0xe04
	v_readlane_b32 s14, v252, 18
	v_cndmask_b32_e32 v0, v210, v0, vcc
	v_lshlrev_b32_e32 v62, 2, v0
	v_xor_b32_e32 v0, 32, v210
	v_cmp_lt_i32_e32 vcc, v0, v1
	v_mov_b32_e32 v1, 0
	v_mov_b32_e32 v3, v1
	v_cndmask_b32_e32 v0, v210, v0, vcc
	v_lshlrev_b32_e32 v63, 2, v0
	v_and_b32_e32 v0, 0x3f0, v144
	v_or_b32_e32 v2, 0x1000, v0
	v_lshl_add_u64 v[8:9], s[10:11], 0, v[2:3]
	v_lshl_add_u64 v[10:11], s[12:13], 0, v[2:3]
	v_or_b32_e32 v2, 0x1400, v0
	v_lshl_add_u64 v[4:5], s[10:11], 0, v[0:1]
	v_lshl_add_u64 v[6:7], s[12:13], 0, v[0:1]
	v_lshl_add_u64 v[12:13], s[10:11], 0, v[2:3]
	v_lshl_add_u64 v[14:15], s[12:13], 0, v[2:3]
	v_or_b32_e32 v2, 0x1800, v0
	v_or_b32_e32 v0, 0x1c00, v0
	v_lshl_add_u64 v[20:21], s[10:11], 0, v[0:1]
	v_lshl_add_u64 v[22:23], s[12:13], 0, v[0:1]
	v_lshlrev_b64 v[0:1], 12, v[124:125]
	v_lshl_or_b32 v0, v201, 3, v0
	v_lshl_add_u64 v[0:1], s[90:91], 0, v[0:1]
	v_lshl_add_u64 v[24:25], v[0:1], 0, s[6:7]
	v_lshlrev_b64 v[0:1], 13, v[124:125]
	v_lshl_or_b32 v0, v201, 4, v0
	v_readlane_b32 s15, v252, 19
	s_ashr_i32 s1, s0, 31
	v_lshl_add_u64 v[0:1], s[88:89], 0, v[0:1]
	s_mov_b64 s[6:7], 0x1000
	v_lshl_add_u64 v[16:17], s[10:11], 0, v[2:3]
	v_lshl_add_u64 v[18:19], s[12:13], 0, v[2:3]
	s_lshl_b64 s[10:11], s[0:1], 12
	v_lshl_add_u64 v[26:27], v[0:1], 0, s[6:7]
	s_lshl_b64 s[12:13], s[0:1], 13
	s_mov_b64 s[14:15], 0
	v_mov_b32_e32 v64, 0x3727c5ac
	s_mov_b32 s1, 0x800000
	s_movk_i32 s3, 0x41ff
	v_mov_b32_e32 v65, v124
	v_readlane_b32 s16, v252, 20
	v_readlane_b32 s17, v252, 21
	v_readlane_b32 s18, v252, 22
	v_readlane_b32 s19, v252, 23
	v_readlane_b32 s20, v252, 24
	v_readlane_b32 s21, v252, 25
	v_readlane_b32 s26, v252, 30
	v_readlane_b32 s27, v252, 31
	global_load_dwordx4 v[128:131], v[4:5], off
	global_load_dwordx4 v[132:135], v[6:7], off
	global_load_dwordx4 v[136:139], v[4:5], off offset:1024
	global_load_dwordx4 v[140:143], v[6:7], off offset:1024
	global_load_dwordx4 v[148:151], v[4:5], off offset:2048
	global_load_dwordx4 v[152:155], v[6:7], off offset:2048
	global_load_dwordx4 v[156:159], v[4:5], off offset:3072
	global_load_dwordx4 v[160:163], v[6:7], off offset:3072
	global_load_dwordx4 v[164:167], v[8:9], off
	global_load_dwordx4 v[168:171], v[10:11], off
	global_load_dwordx4 v[172:175], v[12:13], off
	global_load_dwordx4 v[176:179], v[14:15], off
	global_load_dwordx4 v[180:183], v[16:17], off
	global_load_dwordx4 v[184:187], v[18:19], off
	global_load_dwordx4 v[188:191], v[20:21], off
	global_load_dwordx4 v[192:195], v[22:23], off
	s_waitcnt vmcnt(0)
	s_branch .LBB0_2651

; __device__ __forceinline__ void ln_phase(const Params& P, const float* g, const float* b, bf16_t* xb) {
;     ...
;         float* y = P.out + O_Y + (size_t)row * 2048;
;         float4 v[8]; float s = 0.f;
; #pragma unroll
;         for (int i = 0; i < 8; ++i) { v[i] = *(const float4*)(y + (i * 64 + lane) * 4); s += (v[i].x + v[i].y) + (v[i].z + v[i].w); }
;         s = halfsum32(s); s += __shfl_xor(s, 32);
;         const float mu = s * (1.0f / 2048.0f); float q = 0.f;
; #pragma unroll
;         for (int i = 0; i < 8; ++i) { v[i].x -= mu; v[i].y -= mu; v[i].z -= mu; v[i].w -= mu; q += (v[i].x * v[i].x + v[i].y * v[i].y) + (v[i].z * v[i].z + v[i].w * v[i].w); }
;         q = halfsum32(q); q += __shfl_xor(q, 32);
.LBB0_2651:
	global_load_dwordx4 v[0:3], v[26:27], off offset:2048
	global_load_dwordx4 v[28:31], v[26:27], off offset:1024
	global_load_dwordx4 v[32:35], v[26:27], off offset:-1024
	global_load_dwordx4 v[36:39], v[26:27], off offset:-2048
	global_load_dwordx4 v[40:43], v[26:27], off offset:-4096
	global_load_dwordx4 v[44:47], v[26:27], off offset:-3072
	global_load_dwordx4 v[66:69], v[26:27], off
	global_load_dwordx4 v[70:73], v[26:27], off offset:3072
	s_waitcnt vmcnt(7)
	v_mov_b32_e32 v48, v1
	s_waitcnt vmcnt(6)
	v_mov_b32_e32 v52, v28
	v_mov_b32_e32 v53, v30
	v_mov_b32_e32 v54, v29
	v_mov_b32_e32 v55, v31
	s_waitcnt vmcnt(5)
	v_mov_b32_e32 v56, v33
	v_mov_b32_e32 v74, v35
	s_waitcnt vmcnt(4)
	v_mov_b32_e32 v76, v36
	v_mov_b32_e32 v77, v38
	v_mov_b32_e32 v78, v37
	v_mov_b32_e32 v79, v39
	s_waitcnt vmcnt(3)
	v_mov_b32_e32 v80, v40
	s_waitcnt vmcnt(2)
	v_mov_b32_e32 v81, v44
	v_mov_b32_e32 v82, v41
	v_mov_b32_e32 v83, v45
	v_mov_b32_e32 v84, v42
	v_mov_b32_e32 v85, v46
	v_mov_b32_e32 v86, v43
	v_mov_b32_e32 v87, v47
	v_pk_add_f32 v[52:53], v[52:53], v[54:55]
	v_pk_add_f32 v[54:55], v[32:33], v[56:57]
	v_pk_add_f32 v[56:57], v[34:35], v[74:75]
	v_pk_add_f32 v[74:75], v[76:77], v[78:79]
	v_pk_add_f32 v[76:77], v[80:81], v[82:83]
	v_pk_add_f32 v[78:79], v[84:85], v[86:87]
	s_waitcnt vmcnt(1)
	v_mov_b32_e32 v49, v66
	v_pk_add_f32 v[76:77], v[76:77], v[78:79]
	v_pk_add_f32 v[88:89], v[0:1], v[48:49]
	v_pk_add_f32 v[74:75], v[74:75], v[74:75] op_sel:[0,1] op_sel_hi:[1,0]
	v_add_f32_e32 v48, 0, v76
	v_mov_b32_e32 v55, v68
	v_mov_b32_e32 v57, v69
	v_mov_b32_e32 v75, v67
	v_add_f32_e32 v48, v48, v77
	v_pk_add_f32 v[54:55], v[54:55], v[56:57]
	v_pk_add_f32 v[48:49], v[48:49], v[74:75]
	v_mov_b32_e32 v50, v3
	v_pk_add_f32 v[48:49], v[48:49], v[54:55]
	v_pk_add_f32 v[50:51], v[2:3], v[50:51]
	v_pk_add_f32 v[52:53], v[52:53], v[52:53] op_sel:[0,1] op_sel_hi:[1,0]
	v_pk_add_f32 v[48:49], v[48:49], v[48:49] op_sel:[0,1] op_sel_hi:[1,0]
	s_waitcnt vmcnt(0)
	v_mov_b32_e32 v89, v72
	v_mov_b32_e32 v51, v73
	v_mov_b32_e32 v53, v71
	v_mov_b32_e32 v49, v70
	v_pk_add_f32 v[50:51], v[88:89], v[50:51]
	v_pk_add_f32 v[48:49], v[48:49], v[52:53]
	s_nop 1
	v_mov_b64_e32 v[74:75], v[128:129]
	v_mov_b64_e32 v[76:77], v[130:131]
	s_nop 1
	v_mov_b64_e32 v[78:79], v[132:133]
	v_mov_b64_e32 v[80:81], v[134:135]
	v_pk_add_f32 v[48:49], v[48:49], v[50:51]
	s_nop 0
	v_add_f32_e32 v48, v48, v49
	ds_bpermute_b32 v49, v58, v48
	s_waitcnt lgkmcnt(0)
	v_add_f32_e32 v48, v48, v49
	ds_bpermute_b32 v49, v59, v48
	s_waitcnt lgkmcnt(0)
	v_add_f32_e32 v48, v48, v49
	ds_bpermute_b32 v49, v60, v48
	s_waitcnt lgkmcnt(0)
	v_add_f32_e32 v48, v48, v49
	ds_bpermute_b32 v49, v61, v48
	s_waitcnt lgkmcnt(0)
	v_add_f32_e32 v48, v48, v49
	ds_bpermute_b32 v49, v62, v48
	s_waitcnt lgkmcnt(0)
	v_add_f32_e32 v48, v48, v49
	ds_bpermute_b32 v49, v63, v48
	s_waitcnt lgkmcnt(0)
	v_add_f32_e32 v48, v48, v49
	v_mul_f32_e32 v48, 0x3a000000, v48
	v_pk_add_f32 v[82:83], v[40:41], v[48:49] op_sel_hi:[1,0] neg_lo:[0,1] neg_hi:[0,1]
	v_pk_add_f32 v[84:85], v[42:43], v[48:49] op_sel_hi:[1,0] neg_lo:[0,1] neg_hi:[0,1]
	v_pk_add_f32 v[54:55], v[44:45], v[48:49] op_sel_hi:[1,0] neg_lo:[0,1] neg_hi:[0,1]
	v_pk_add_f32 v[56:57], v[46:47], v[48:49] op_sel_hi:[1,0] neg_lo:[0,1] neg_hi:[0,1]
	v_pk_add_f32 v[50:51], v[36:37], v[48:49] op_sel_hi:[1,0] neg_lo:[0,1] neg_hi:[0,1]
	v_pk_add_f32 v[52:53], v[38:39], v[48:49] op_sel_hi:[1,0] neg_lo:[0,1] neg_hi:[0,1]
	v_pk_add_f32 v[46:47], v[34:35], v[48:49] op_sel_hi:[1,0] neg_lo:[0,1] neg_hi:[0,1]
	v_pk_add_f32 v[40:41], v[66:67], v[48:49] op_sel_hi:[1,0] neg_lo:[0,1] neg_hi:[0,1]
	v_pk_add_f32 v[34:35], v[2:3], v[48:49] op_sel_hi:[1,0] neg_lo:[0,1] neg_hi:[0,1]
	v_mov_b32_e32 v2, v83
	v_mov_b32_e32 v3, v55
	v_mov_b32_e32 v66, v85
	v_mov_b32_e32 v67, v57
	v_pk_add_f32 v[44:45], v[32:33], v[48:49] op_sel_hi:[1,0] neg_lo:[0,1] neg_hi:[0,1]
	v_pk_add_f32 v[42:43], v[68:69], v[48:49] op_sel_hi:[1,0] neg_lo:[0,1] neg_hi:[0,1]
	v_pk_add_f32 v[36:37], v[28:29], v[48:49] op_sel_hi:[1,0] neg_lo:[0,1] neg_hi:[0,1]
	v_pk_add_f32 v[38:39], v[30:31], v[48:49] op_sel_hi:[1,0] neg_lo:[0,1] neg_hi:[0,1]
	v_pk_add_f32 v[32:33], v[0:1], v[48:49] op_sel_hi:[1,0] neg_lo:[0,1] neg_hi:[0,1]
	v_pk_add_f32 v[28:29], v[70:71], v[48:49] op_sel_hi:[1,0] neg_lo:[0,1] neg_hi:[0,1]
	v_pk_add_f32 v[30:31], v[72:73], v[48:49] op_sel_hi:[1,0] neg_lo:[0,1] neg_hi:[0,1]
	v_mov_b32_e32 v0, v82
	v_mov_b32_e32 v1, v54
	v_mov_b32_e32 v48, v84
	v_mov_b32_e32 v49, v56
	v_mov_b32_e32 v70, v51
	v_mov_b32_e32 v71, v53
	v_pk_mul_f32 v[2:3], v[2:3], v[2:3]
	v_pk_mul_f32 v[66:67], v[66:67], v[66:67]
	v_mov_b32_e32 v68, v50
	v_mov_b32_e32 v69, v52
	v_pk_mul_f32 v[70:71], v[70:71], v[70:71]
	v_pk_fma_f32 v[0:1], v[0:1], v[0:1], v[2:3]
	v_pk_fma_f32 v[2:3], v[48:49], v[48:49], v[66:67]
	v_mul_f32_e32 v72, v44, v44
	v_mul_f32_e32 v86, v46, v46
	v_pk_fma_f32 v[48:49], v[68:69], v[68:69], v[70:71]
	v_pk_add_f32 v[0:1], v[0:1], v[2:3]
	v_pk_mul_f32 v[88:89], v[40:41], v[40:41]
	v_pk_mul_f32 v[90:91], v[42:43], v[42:43]
	v_pk_fma_f32 v[72:73], v[44:45], v[44:45], v[72:73] op_sel_hi:[1,1,0]
	v_pk_fma_f32 v[86:87], v[46:47], v[46:47], v[86:87] op_sel_hi:[1,1,0]
	v_pk_add_f32 v[2:3], v[48:49], v[48:49] op_sel_hi:[0,1]
	v_pk_add_f32 v[0:1], v[0:1], v[0:1] op_sel_hi:[0,1]
	v_mov_b32_e32 v94, v37
	v_mov_b32_e32 v95, v39
	v_mov_b32_e32 v72, v88
	v_mov_b32_e32 v86, v89
	v_mov_b32_e32 v2, v90
	v_mov_b32_e32 v0, v91
	v_mov_b32_e32 v92, v36
	v_mov_b32_e32 v93, v38
	v_pk_mul_f32 v[94:95], v[94:95], v[94:95]
	v_pk_add_f32 v[48:49], v[72:73], v[86:87]
	v_pk_add_f32 v[0:1], v[2:3], v[0:1]
	v_mul_f32_e32 v96, v32, v32
	v_mul_f32_e32 v98, v34, v34
	v_pk_fma_f32 v[66:67], v[92:93], v[92:93], v[94:95]
	v_pk_add_f32 v[0:1], v[48:49], v[0:1]
	v_pk_mul_f32 v[100:101], v[28:29], v[28:29]
	v_pk_mul_f32 v[102:103], v[30:31], v[30:31]
	v_pk_fma_f32 v[96:97], v[32:33], v[32:33], v[96:97] op_sel_hi:[1,1,0]
	v_pk_fma_f32 v[98:99], v[34:35], v[34:35], v[98:99] op_sel_hi:[1,1,0]
	v_pk_add_f32 v[66:67], v[66:67], v[66:67] op_sel_hi:[0,1]
	v_pk_add_f32 v[0:1], v[0:1], v[0:1] op_sel_hi:[0,1]
	v_mov_b32_e32 v96, v100
	v_mov_b32_e32 v98, v101
	v_mov_b32_e32 v66, v102
	v_mov_b32_e32 v0, v103
	v_pk_add_f32 v[68:69], v[96:97], v[98:99]
	v_pk_add_f32 v[0:1], v[66:67], v[0:1]
	s_nop 0
	v_pk_add_f32 v[0:1], v[68:69], v[0:1]
	s_nop 0
	v_add_f32_e32 v0, v0, v1
	ds_bpermute_b32 v1, v58, v0
	s_waitcnt lgkmcnt(0)
; __device__ __forceinline__ unsigned pk_bf16(float lo, float hi) { unsigned r; asm("v_cvt_pk_bf16_f32 %0, %1, %2" : "=v"(r) : "v"(lo), "v"(hi)); return r; }
; __device__ __forceinline__ void ln_phase(const Params& P, const float* g, const float* b, bf16_t* xb) {
;     ...
;         q = halfsum32(q); q += __shfl_xor(q, 32);
;         const float rstd = rsqrtf(q * (1.0f / 2048.0f) + 1e-5f);
; #pragma unroll
;         for (int i = 0; i < 8; ++i) { const int c = (i * 64 + lane) * 4; const float4 gg = *(const float4*)(g + c), bb = *(const float4*)(b + c);
;             float4 o; o.x = v[i].x * rstd * gg.x + bb.x; o.y = v[i].y * rstd * gg.y + bb.y; o.z = v[i].z * rstd * gg.z + bb.z; o.w = v[i].w * rstd * gg.w + bb.w;
;             *(float4*)(y + c) = o;
;             if (xb) { uint2 w; w.x = pk_bf16(o.x, o.y); w.y = pk_bf16(o.z, o.w); *(uint2*)(xb + (size_t)row * 2048 + c) = w; } }
	v_add_f32_e32 v0, v0, v1
	ds_bpermute_b32 v1, v59, v0
	s_waitcnt lgkmcnt(0)
	v_add_f32_e32 v0, v0, v1
	ds_bpermute_b32 v1, v60, v0
	s_waitcnt lgkmcnt(0)
	v_add_f32_e32 v0, v0, v1
	ds_bpermute_b32 v1, v61, v0
	s_waitcnt lgkmcnt(0)
	v_add_f32_e32 v0, v0, v1
	ds_bpermute_b32 v1, v62, v0
	s_waitcnt lgkmcnt(0)
	v_add_f32_e32 v0, v0, v1
	ds_bpermute_b32 v1, v63, v0
	s_waitcnt lgkmcnt(0)
	v_add_f32_e32 v0, v0, v1
	v_fmamk_f32 v0, v0, 0x3a000000, v64
	v_mul_f32_e32 v1, 0x4b800000, v0
	v_cmp_gt_f32_e32 vcc, s1, v0
	s_nop 1
	v_cndmask_b32_e32 v0, v0, v1, vcc
	v_rsq_f32_e32 v0, v0
	v_cndmask_b32_e64 v1, 0, 1, s[52:53]
	v_cmp_ne_u32_e64 s[6:7], 1, v1
	v_mul_f32_e32 v1, 0x45800000, v0
	v_cndmask_b32_e32 v48, v0, v1, vcc
	v_pk_mul_f32 v[0:1], v[82:83], v[48:49] op_sel_hi:[1,0]
	v_pk_mul_f32 v[2:3], v[84:85], v[48:49] op_sel_hi:[1,0]
	v_pk_fma_f32 v[0:1], v[74:75], v[0:1], v[78:79]
	v_pk_fma_f32 v[2:3], v[76:77], v[2:3], v[80:81]
	s_andn2_b64 vcc, exec, s[52:53]
	global_store_dwordx4 v[26:27], v[0:3], off offset:-4096
	s_cbranch_vccnz .LBB0_2653
	s_nop 0
	v_cvt_pk_bf16_f32 v0, v0, v1
	v_cvt_pk_bf16_f32 v1, v2, v3
	global_store_dwordx2 v[24:25], v[0:1], off offset:-3588
.LBB0_2653:
	s_nop 1
	v_mov_b64_e32 v[0:1], v[136:137]
	v_mov_b64_e32 v[2:3], v[138:139]
	s_nop 0
	s_nop 1
	v_mov_b64_e32 v[66:67], v[140:141]
	v_mov_b64_e32 v[68:69], v[142:143]
	v_mov_b32_e32 v49, v48
	v_pk_mul_f32 v[54:55], v[54:55], v[48:49]
	v_pk_mul_f32 v[56:57], v[56:57], v[48:49]
	s_and_b64 vcc, exec, s[6:7]
	v_pk_fma_f32 v[0:1], v[54:55], v[0:1], v[66:67]
	v_pk_fma_f32 v[2:3], v[56:57], v[2:3], v[68:69]
	global_store_dwordx4 v[26:27], v[0:3], off offset:-3072
	s_cbranch_vccnz .LBB0_2655
	s_nop 0
	v_cvt_pk_bf16_f32 v0, v0, v1
	v_cvt_pk_bf16_f32 v1, v2, v3
	global_store_dwordx2 v[24:25], v[0:1], off offset:-3076
.LBB0_2655:
	s_nop 1
	v_mov_b64_e32 v[0:1], v[148:149]
	v_mov_b64_e32 v[2:3], v[150:151]
	s_nop 0
	s_nop 1
	v_mov_b64_e32 v[54:55], v[152:153]
	v_mov_b64_e32 v[56:57], v[154:155]
	v_pk_mul_f32 v[50:51], v[50:51], v[48:49]
	v_pk_mul_f32 v[52:53], v[52:53], v[48:49]
	s_and_b64 vcc, exec, s[6:7]
	v_pk_fma_f32 v[0:1], v[50:51], v[0:1], v[54:55]
	v_pk_fma_f32 v[2:3], v[52:53], v[2:3], v[56:57]
	global_store_dwordx4 v[26:27], v[0:3], off offset:-2048
	s_cbranch_vccnz .LBB0_2657
	s_nop 0
	v_cvt_pk_bf16_f32 v0, v0, v1
	v_cvt_pk_bf16_f32 v1, v2, v3
	global_store_dwordx2 v[24:25], v[0:1], off offset:-2564
.LBB0_2657:
	s_nop 1
	v_mov_b64_e32 v[0:1], v[156:157]
	v_mov_b64_e32 v[2:3], v[158:159]
	s_nop 0
	s_nop 1
	v_mov_b64_e32 v[50:51], v[160:161]
	v_mov_b64_e32 v[52:53], v[162:163]
	v_pk_mul_f32 v[44:45], v[44:45], v[48:49]
	v_pk_mul_f32 v[46:47], v[46:47], v[48:49]
	s_and_b64 vcc, exec, s[6:7]
	v_pk_fma_f32 v[0:1], v[44:45], v[0:1], v[50:51]
	v_pk_fma_f32 v[2:3], v[46:47], v[2:3], v[52:53]
	global_store_dwordx4 v[26:27], v[0:3], off offset:-1024
	s_cbranch_vccnz .LBB0_2659
	s_nop 0
	v_cvt_pk_bf16_f32 v0, v0, v1
	v_cvt_pk_bf16_f32 v1, v2, v3
	global_store_dwordx2 v[24:25], v[0:1], off offset:-2052
.LBB0_2659:
	s_nop 1
	v_mov_b64_e32 v[0:1], v[164:165]
	v_mov_b64_e32 v[2:3], v[166:167]
	s_nop 0
	s_nop 1
	v_mov_b64_e32 v[44:45], v[168:169]
	v_mov_b64_e32 v[46:47], v[170:171]
	v_pk_mul_f32 v[40:41], v[40:41], v[48:49]
	v_pk_mul_f32 v[42:43], v[42:43], v[48:49]
	s_and_b64 vcc, exec, s[6:7]
	v_pk_fma_f32 v[0:1], v[40:41], v[0:1], v[44:45]
	v_pk_fma_f32 v[2:3], v[42:43], v[2:3], v[46:47]
	global_store_dwordx4 v[26:27], v[0:3], off
	s_cbranch_vccnz .LBB0_2661
	s_nop 0
	v_cvt_pk_bf16_f32 v0, v0, v1
	v_cvt_pk_bf16_f32 v1, v2, v3
	global_store_dwordx2 v[24:25], v[0:1], off offset:-1540
.LBB0_2661:
	s_nop 1
	v_mov_b64_e32 v[0:1], v[172:173]
	v_mov_b64_e32 v[2:3], v[174:175]
	s_nop 0
	s_nop 1
	v_mov_b64_e32 v[40:41], v[176:177]
	v_mov_b64_e32 v[42:43], v[178:179]
	v_pk_mul_f32 v[36:37], v[36:37], v[48:49]
	v_pk_mul_f32 v[38:39], v[38:39], v[48:49]
	s_and_b64 vcc, exec, s[6:7]
	v_pk_fma_f32 v[0:1], v[36:37], v[0:1], v[40:41]
	v_pk_fma_f32 v[2:3], v[38:39], v[2:3], v[42:43]
	global_store_dwordx4 v[26:27], v[0:3], off offset:1024
	s_cbranch_vccnz .LBB0_2663
	s_nop 0
	v_cvt_pk_bf16_f32 v0, v0, v1
	v_cvt_pk_bf16_f32 v1, v2, v3
	global_store_dwordx2 v[24:25], v[0:1], off offset:-1028
.LBB0_2663:
	s_nop 1
	v_mov_b64_e32 v[0:1], v[180:181]
	v_mov_b64_e32 v[2:3], v[182:183]
	s_nop 0
	s_nop 1
	v_mov_b64_e32 v[36:37], v[184:185]
	v_mov_b64_e32 v[38:39], v[186:187]
	v_pk_mul_f32 v[32:33], v[32:33], v[48:49]
	v_pk_mul_f32 v[34:35], v[34:35], v[48:49]
	s_and_b64 vcc, exec, s[6:7]
	v_pk_fma_f32 v[0:1], v[32:33], v[0:1], v[36:37]
	v_pk_fma_f32 v[2:3], v[34:35], v[2:3], v[38:39]
	global_store_dwordx4 v[26:27], v[0:3], off offset:2048
	s_cbranch_vccnz .LBB0_2665
	s_nop 0
	v_cvt_pk_bf16_f32 v0, v0, v1
	v_cvt_pk_bf16_f32 v1, v2, v3
	global_store_dwordx2 v[24:25], v[0:1], off offset:-516
.LBB0_2665:
	s_nop 1
	v_mov_b64_e32 v[0:1], v[188:189]
	v_mov_b64_e32 v[2:3], v[190:191]
	s_nop 0
	s_nop 1
	v_mov_b64_e32 v[32:33], v[192:193]
	v_mov_b64_e32 v[34:35], v[194:195]
	v_pk_mul_f32 v[28:29], v[28:29], v[48:49]
	v_pk_mul_f32 v[30:31], v[30:31], v[48:49]
	s_and_b64 vcc, exec, s[6:7]
	v_pk_fma_f32 v[0:1], v[28:29], v[0:1], v[32:33]
	v_pk_fma_f32 v[2:3], v[30:31], v[2:3], v[34:35]
	global_store_dwordx4 v[26:27], v[0:3], off offset:3072
	s_cbranch_vccnz .LBB0_2650
	s_nop 0
	v_cvt_pk_bf16_f32 v0, v0, v1
	v_cvt_pk_bf16_f32 v1, v2, v3
	global_store_dwordx2 v[24:25], v[0:1], off offset:-4
	s_branch .LBB0_2650
